# global prefetch issue moved to after the first four MFMAs of the block
# speedup vs baseline: 1.0118x; 1.0005x over previous
.LBB0_542:
	s_cmp_gt_u32 s52, s51
	s_cbranch_scc1 .Lh1_skip
	s_mul_i32 s61, s25, 0x2200
	s_and_b32 s42, s52, 2
	s_mulk_i32 s42, 0x3400
	v_add_u32_e32 v0, s42, v160
	v_add_u32_e32 v242, s61, v161
	v_add_u32_e32 v163, 0xe000, v242
	v_add_u32_e32 v242, 0xd000, v242
	ds_read_b128 v[82:85], v0 offset:13312
	ds_read_b128 v[98:101], v0 offset:19968
	ds_read_b128 v[164:167], v0 offset:13344
	ds_read_b128 v[168:171], v0 offset:20000
	ds_read2_b64 v[238:241], v242 offset0:0 offset1:2
	ds_read2_b64 v[234:237], v163 offset0:32 offset1:34
	ds_read_b128 v[172:175], v0 offset:13376
	ds_read_b128 v[176:179], v0 offset:20032
	ds_read_b128 v[180:183], v0 offset:13408
	ds_read_b128 v[184:187], v0 offset:20064
	ds_read_b128 v[188:191], v0 offset:13440
	ds_read_b128 v[192:195], v0 offset:20096
	ds_read_b128 v[196:199], v0 offset:13472
	ds_read_b128 v[220:223], v0 offset:20128
	v_exp_f32_e32 v50, v50
	v_exp_f32_e32 v51, v51
	v_exp_f32_e32 v52, v52
	v_exp_f32_e32 v53, v53
	v_exp_f32_e32 v54, v54
	v_exp_f32_e32 v55, v55
	v_exp_f32_e32 v56, v56
	v_exp_f32_e32 v57, v57
	s_waitcnt lgkmcnt(13)
	v_mfma_f32_32x32x16_bf16 v[82:97], v[82:85], v[122:125], 0
	v_cvt_pk_bf16_f32 v224, v50, v51
	v_cvt_pk_bf16_f32 v225, v52, v53
	v_cvt_pk_bf16_f32 v226, v54, v55
	v_cvt_pk_bf16_f32 v227, v56, v57
	v_exp_f32_e32 v58, v58
	v_add_f32_e32 v200, v50, v51
	s_waitcnt lgkmcnt(12)
	v_mfma_f32_32x32x16_bf16 v[98:113], v[98:101], v[122:125], 0
	v_exp_f32_e32 v59, v59
	v_exp_f32_e32 v60, v60
	v_add_f32_e32 v201, v52, v53
	v_exp_f32_e32 v61, v61
	s_waitcnt lgkmcnt(11)
	v_mfma_f32_32x32x16_bf16 v[82:97], v[164:167], v[126:129], v[82:97]
	v_exp_f32_e32 v62, v62
	v_add_f32_e32 v200, v200, v54
	v_exp_f32_e32 v63, v63
	v_add_f32_e32 v201, v201, v55
	v_exp_f32_e32 v64, v64
	s_waitcnt lgkmcnt(10)
	v_mfma_f32_32x32x16_bf16 v[98:113], v[168:171], v[126:129], v[98:113]
	ds_read2_b64 v[164:167], v242 offset0:4 offset1:6
	ds_read2_b64 v[168:171], v163 offset0:36 offset1:38
	v_add_f32_e32 v200, v200, v56
	v_exp_f32_e32 v65, v65
	v_add_f32_e32 v201, v201, v57
	v_cvt_pk_bf16_f32 v228, v58, v59
	v_cvt_pk_bf16_f32 v229, v60, v61
	s_add_i32 s60, s52, 3
	s_cmp_lt_u32 s60, s48
	s_cselect_b64 s[58:59], -1, 0
	s_cmp_ge_u32 s60, s48
	s_cbranch_scc1 .Lp1a_546
	s_waitcnt vmcnt(0)
	v_lshl_add_u64 v[2:3], s[54:55], 0, v[154:155]
	v_add_co_u32_e32 v2, vcc, 0xbe09000, v2
	s_nop 1
	v_addc_co_u32_e32 v3, vcc, 0, v3, vcc
	global_load_dwordx4 v[2:5], v[2:3], off
	s_and_saveexec_b64 s[42:43], s[40:41]
	s_cbranch_execz .Lp1a_545
	v_lshl_add_u64 v[10:11], s[54:55], 0, v[152:153]
	v_add_co_u32_e32 v10, vcc, 0xbe09000, v10
	s_nop 1
	v_addc_co_u32_e32 v11, vcc, 0, v11, vcc
	global_load_dwordx4 v[10:13], v[10:11], off

.Lp1a_end:
	s_waitcnt lgkmcnt(11)
	v_mfma_f32_32x32x16_bf16 v[18:33], v[238:241], v[224:227], v[18:33]
	v_cvt_pk_bf16_f32 v230, v62, v63
	v_cvt_pk_bf16_f32 v231, v64, v65
	v_exp_f32_e32 v66, v66
	v_add_f32_e32 v200, v200, v58
	v_exp_f32_e32 v67, v67
	v_add_f32_e32 v201, v201, v59
	s_waitcnt lgkmcnt(10)
	v_mfma_f32_32x32x16_bf16 v[34:49], v[234:237], v[224:227], v[34:49]
	v_exp_f32_e32 v68, v68
	v_add_f32_e32 v200, v200, v60
	v_exp_f32_e32 v69, v69
	v_add_f32_e32 v201, v201, v61
	v_exp_f32_e32 v70, v70
	s_waitcnt lgkmcnt(9)
	v_mfma_f32_32x32x16_bf16 v[82:97], v[172:175], v[134:137], v[82:97]
	v_add_f32_e32 v200, v200, v62
	v_exp_f32_e32 v71, v71
	v_add_f32_e32 v201, v201, v63
	v_exp_f32_e32 v72, v72
	v_add_f32_e32 v200, v200, v64
	s_waitcnt lgkmcnt(8)
	v_mfma_f32_32x32x16_bf16 v[98:113], v[176:179], v[134:137], v[98:113]
	ds_read2_b64 v[172:175], v242 offset0:8 offset1:10
	ds_read2_b64 v[176:179], v163 offset0:40 offset1:42
	v_exp_f32_e32 v73, v73
	v_add_f32_e32 v201, v201, v65
	v_cvt_pk_bf16_f32 v224, v66, v67
	v_cvt_pk_bf16_f32 v225, v68, v69
	v_cvt_pk_bf16_f32 v226, v70, v71
	s_waitcnt lgkmcnt(3)
	v_mfma_f32_32x32x16_bf16 v[18:33], v[164:167], v[228:231], v[18:33]
	v_cvt_pk_bf16_f32 v227, v72, v73
	v_exp_f32_e32 v74, v74
	v_add_f32_e32 v200, v200, v66
	v_exp_f32_e32 v75, v75
	v_add_f32_e32 v201, v201, v67
	s_waitcnt lgkmcnt(2)
	v_mfma_f32_32x32x16_bf16 v[34:49], v[168:171], v[228:231], v[34:49]
	v_exp_f32_e32 v76, v76
	v_add_f32_e32 v200, v200, v68
	v_exp_f32_e32 v77, v77
	v_add_f32_e32 v201, v201, v69
	v_exp_f32_e32 v78, v78
	s_waitcnt lgkmcnt(9)
	v_mfma_f32_32x32x16_bf16 v[82:97], v[180:183], v[138:141], v[82:97]
	v_add_f32_e32 v200, v200, v70
	v_exp_f32_e32 v79, v79
	v_add_f32_e32 v201, v201, v71
	v_exp_f32_e32 v80, v80
	v_add_f32_e32 v200, v200, v72
	s_waitcnt lgkmcnt(8)
	v_mfma_f32_32x32x16_bf16 v[98:113], v[184:187], v[138:141], v[98:113]
	ds_read2_b64 v[180:183], v242 offset0:12 offset1:14
	ds_read2_b64 v[184:187], v163 offset0:44 offset1:46
	v_exp_f32_e32 v81, v81
	v_add_f32_e32 v201, v201, v73
	v_cvt_pk_bf16_f32 v228, v74, v75
	v_cvt_pk_bf16_f32 v229, v76, v77
	v_cvt_pk_bf16_f32 v230, v78, v79
	s_waitcnt lgkmcnt(3)
	v_mfma_f32_32x32x16_bf16 v[18:33], v[172:175], v[224:227], v[18:33]
	v_cvt_pk_bf16_f32 v231, v80, v81
	v_add_f32_e32 v200, v200, v74
	v_add_f32_e32 v201, v201, v75
	v_add_f32_e32 v200, v200, v76
	v_add_f32_e32 v201, v201, v77
	v_add_f32_e32 v200, v200, v78
	v_add_f32_e32 v201, v201, v79
	v_add_f32_e32 v200, v200, v80
	s_waitcnt lgkmcnt(2)
	v_mfma_f32_32x32x16_bf16 v[34:49], v[176:179], v[224:227], v[34:49]
	v_add_f32_e32 v201, v201, v81
	v_add_f32_e32 v200, v200, v201
	v_add_f32_e32 v162, v162, v200
	s_waitcnt lgkmcnt(9)
	v_mfma_f32_32x32x16_bf16 v[82:97], v[188:191], v[142:145], v[82:97]
	s_waitcnt lgkmcnt(8)
	v_mfma_f32_32x32x16_bf16 v[98:113], v[192:195], v[142:145], v[98:113]
	s_waitcnt lgkmcnt(7)
	v_mfma_f32_32x32x16_bf16 v[82:97], v[196:199], v[146:149], v[82:97]
	s_waitcnt lgkmcnt(6)
	v_mfma_f32_32x32x16_bf16 v[98:113], v[220:223], v[146:149], v[98:113]
	s_waitcnt lgkmcnt(0)
	v_cndmask_b32_e64 v0, 0, 1, s[44:45]
	v_cmp_ne_u32_e64 s[42:43], 1, v0
	s_andn2_b64 vcc, exec, s[44:45]
	s_cbranch_vccnz .Lt1a_mid
	s_and_b32 s44, s53, 2
	s_mulk_i32 s44, 0x3400
	s_add_i32 s62, s44, 0
	v_add_u32_e32 v0, s62, v151
	s_waitcnt vmcnt(0)
	ds_write_b128 v0, v[118:121]
	s_and_saveexec_b64 s[44:45], s[40:41]
	v_add_u32_e32 v0, s62, v159
	ds_write_b128 v0, v[6:9]
	s_or_b64 exec, exec, s[44:45]

.LBB0_556:
	s_add_i32 s61, s25, 1
	s_cmp_lg_u32 s25, 2
	s_cselect_b32 s25, s61, 0
	s_andn2_b64 vcc, exec, s[44:45]
	s_waitcnt lgkmcnt(0)
	s_barrier
	s_cbranch_vccnz .LBB0_572
	s_cmp_ge_u32 s52, s51
	s_cbranch_scc1 .Lh2_skip
	s_andn2_b32 s62, 2, s52
	s_mulk_i32 s62, 0x3400
	v_add_u32_e32 v0, s62, v160
	s_mul_i32 s62, s25, 0x2200
	v_add_u32_e32 v242, s62, v161
	v_add_u32_e32 v163, 0xe000, v242
	v_add_u32_e32 v242, 0xd000, v242
	ds_read_b128 v[50:53], v0 offset:0
	ds_read_b128 v[66:69], v0 offset:6656
	ds_read_b128 v[164:167], v0 offset:32
	ds_read_b128 v[168:171], v0 offset:6688
	ds_read2_b64 v[238:241], v242 offset0:0 offset1:2
	ds_read2_b64 v[234:237], v163 offset0:32 offset1:34
	ds_read_b128 v[172:175], v0 offset:64
	ds_read_b128 v[176:179], v0 offset:6720
	ds_read_b128 v[180:183], v0 offset:96
	ds_read_b128 v[184:187], v0 offset:6752
	ds_read_b128 v[188:191], v0 offset:128
	ds_read_b128 v[192:195], v0 offset:6784
	ds_read_b128 v[196:199], v0 offset:160
	ds_read_b128 v[220:223], v0 offset:6816
	v_exp_f32_e32 v82, v82
	v_exp_f32_e32 v83, v83
	v_exp_f32_e32 v84, v84
	v_exp_f32_e32 v85, v85
	v_exp_f32_e32 v86, v86
	v_exp_f32_e32 v87, v87
	v_exp_f32_e32 v88, v88
	v_exp_f32_e32 v89, v89
	s_waitcnt lgkmcnt(13)
	v_mfma_f32_32x32x16_bf16 v[50:65], v[50:53], v[122:125], 0
	v_cvt_pk_bf16_f32 v224, v82, v83
	v_cvt_pk_bf16_f32 v225, v84, v85
	v_cvt_pk_bf16_f32 v226, v86, v87
	v_cvt_pk_bf16_f32 v227, v88, v89
	v_exp_f32_e32 v90, v90
	v_add_f32_e32 v200, v82, v83
	s_waitcnt lgkmcnt(12)
	v_mfma_f32_32x32x16_bf16 v[66:81], v[66:69], v[122:125], 0
	v_exp_f32_e32 v91, v91
	v_exp_f32_e32 v92, v92
	v_add_f32_e32 v201, v84, v85
	v_exp_f32_e32 v93, v93
	s_waitcnt lgkmcnt(11)
	v_mfma_f32_32x32x16_bf16 v[50:65], v[164:167], v[126:129], v[50:65]
	v_exp_f32_e32 v94, v94
	v_add_f32_e32 v200, v200, v86
	v_exp_f32_e32 v95, v95
	v_add_f32_e32 v201, v201, v87
	v_exp_f32_e32 v96, v96
	s_waitcnt lgkmcnt(10)
	v_mfma_f32_32x32x16_bf16 v[66:81], v[168:171], v[126:129], v[66:81]
	ds_read2_b64 v[164:167], v242 offset0:4 offset1:6
	ds_read2_b64 v[168:171], v163 offset0:36 offset1:38
	v_add_f32_e32 v200, v200, v88
	v_exp_f32_e32 v97, v97
	v_add_f32_e32 v201, v201, v89
	v_cvt_pk_bf16_f32 v228, v90, v91
	v_cvt_pk_bf16_f32 v229, v92, v93
	s_cmp_ge_u32 s52, s5
	s_cbranch_scc1 .Lp2a_561
	s_waitcnt vmcnt(0)
	v_lshl_add_u64 v[118:119], s[54:55], 0, v[154:155]
	v_add_co_u32_e32 v118, vcc, 0xbe0c000, v118
	s_nop 1
	v_addc_co_u32_e32 v119, vcc, 0, v119, vcc
	global_load_dwordx4 v[118:121], v[118:119], off
	s_and_saveexec_b64 s[44:45], s[40:41]
	s_cbranch_execz .Lp2a_560
	v_lshl_add_u64 v[6:7], s[54:55], 0, v[152:153]
	v_add_co_u32_e32 v6, vcc, 0xbe0c000, v6
	s_nop 1
	v_addc_co_u32_e32 v7, vcc, 0, v7, vcc
	global_load_dwordx4 v[6:9], v[6:7], off

.Lp2a_end:
	s_waitcnt lgkmcnt(11)
	v_mfma_f32_32x32x16_bf16 v[18:33], v[238:241], v[224:227], v[18:33]
	v_cvt_pk_bf16_f32 v230, v94, v95
	v_cvt_pk_bf16_f32 v231, v96, v97
	v_exp_f32_e32 v98, v98
	v_add_f32_e32 v200, v200, v90
	v_exp_f32_e32 v99, v99
	v_add_f32_e32 v201, v201, v91
	s_waitcnt lgkmcnt(10)
	v_mfma_f32_32x32x16_bf16 v[34:49], v[234:237], v[224:227], v[34:49]
	v_exp_f32_e32 v100, v100
	v_add_f32_e32 v200, v200, v92
	v_exp_f32_e32 v101, v101
	v_add_f32_e32 v201, v201, v93
	v_exp_f32_e32 v102, v102
	s_waitcnt lgkmcnt(9)
	v_mfma_f32_32x32x16_bf16 v[50:65], v[172:175], v[134:137], v[50:65]
	v_add_f32_e32 v200, v200, v94
	v_exp_f32_e32 v103, v103
	v_add_f32_e32 v201, v201, v95
	v_exp_f32_e32 v104, v104
	v_add_f32_e32 v200, v200, v96
	s_waitcnt lgkmcnt(8)
	v_mfma_f32_32x32x16_bf16 v[66:81], v[176:179], v[134:137], v[66:81]
	ds_read2_b64 v[172:175], v242 offset0:8 offset1:10
	ds_read2_b64 v[176:179], v163 offset0:40 offset1:42
	v_exp_f32_e32 v105, v105
	v_add_f32_e32 v201, v201, v97
	v_cvt_pk_bf16_f32 v224, v98, v99
	v_cvt_pk_bf16_f32 v225, v100, v101
	v_cvt_pk_bf16_f32 v226, v102, v103
	s_waitcnt lgkmcnt(3)
	v_mfma_f32_32x32x16_bf16 v[18:33], v[164:167], v[228:231], v[18:33]
	v_cvt_pk_bf16_f32 v227, v104, v105
	v_exp_f32_e32 v106, v106
	v_add_f32_e32 v200, v200, v98
	v_exp_f32_e32 v107, v107
	v_add_f32_e32 v201, v201, v99
	s_waitcnt lgkmcnt(2)
	v_mfma_f32_32x32x16_bf16 v[34:49], v[168:171], v[228:231], v[34:49]
	v_exp_f32_e32 v108, v108
	v_add_f32_e32 v200, v200, v100
	v_exp_f32_e32 v109, v109
	v_add_f32_e32 v201, v201, v101
	v_exp_f32_e32 v110, v110
	s_waitcnt lgkmcnt(9)
	v_mfma_f32_32x32x16_bf16 v[50:65], v[180:183], v[138:141], v[50:65]
	v_add_f32_e32 v200, v200, v102
	v_exp_f32_e32 v111, v111
	v_add_f32_e32 v201, v201, v103
	v_exp_f32_e32 v112, v112
	v_add_f32_e32 v200, v200, v104
	s_waitcnt lgkmcnt(8)
	v_mfma_f32_32x32x16_bf16 v[66:81], v[184:187], v[138:141], v[66:81]
	ds_read2_b64 v[180:183], v242 offset0:12 offset1:14
	ds_read2_b64 v[184:187], v163 offset0:44 offset1:46
	v_exp_f32_e32 v113, v113
	v_add_f32_e32 v201, v201, v105
	v_cvt_pk_bf16_f32 v228, v106, v107
	v_cvt_pk_bf16_f32 v229, v108, v109
	v_cvt_pk_bf16_f32 v230, v110, v111
	s_waitcnt lgkmcnt(3)
	v_mfma_f32_32x32x16_bf16 v[18:33], v[172:175], v[224:227], v[18:33]
	v_cvt_pk_bf16_f32 v231, v112, v113
	v_add_f32_e32 v200, v200, v106
	v_add_f32_e32 v201, v201, v107
	v_add_f32_e32 v200, v200, v108
	v_add_f32_e32 v201, v201, v109
	v_add_f32_e32 v200, v200, v110
	v_add_f32_e32 v201, v201, v111
	v_add_f32_e32 v200, v200, v112
	s_waitcnt lgkmcnt(2)
	v_mfma_f32_32x32x16_bf16 v[34:49], v[176:179], v[224:227], v[34:49]
	v_add_f32_e32 v201, v201, v113
	v_add_f32_e32 v200, v200, v201
	v_add_f32_e32 v162, v162, v200
	s_waitcnt lgkmcnt(9)
	v_mfma_f32_32x32x16_bf16 v[50:65], v[188:191], v[142:145], v[50:65]
	s_waitcnt lgkmcnt(8)
	v_mfma_f32_32x32x16_bf16 v[66:81], v[192:195], v[142:145], v[66:81]
	s_waitcnt lgkmcnt(7)
	v_mfma_f32_32x32x16_bf16 v[50:65], v[196:199], v[146:149], v[50:65]
	s_waitcnt lgkmcnt(6)
	v_mfma_f32_32x32x16_bf16 v[66:81], v[220:223], v[146:149], v[66:81]
	s_waitcnt lgkmcnt(0)
	s_mul_i32 s58, s25, 0x2200
	s_and_b64 vcc, exec, s[44:45]
	s_cbranch_vccnz .Lt2a_mid
	s_and_b32 s44, s60, 3
	s_mulk_i32 s44, 0x3400
	s_add_i32 s52, s44, 0
	v_add_u32_e32 v0, s52, v151
	s_waitcnt vmcnt(0)
	ds_write_b128 v0, v[2:5]
	s_and_saveexec_b64 s[44:45], s[40:41]
	v_add_u32_e32 v0, s52, v159
	ds_write_b128 v0, v[10:13]
	s_or_b64 exec, exec, s[44:45]
